# v31: P5 ssd_out initial tile staging de-serialized (all C/B/acs loads issued before one wait) on top of v28
# speedup vs baseline: 1.0070x; 1.0070x over previous
.LBB0_1272:
	s_ashr_i32 s25, s74, 7
	s_bfe_u32 s26, s74, 0x50002
	s_and_b32 s10, s74, 1
	s_lshl_b32 s33, s25, 12
	s_lshl_b32 s0, s26, 7
	s_or_b32 s72, s0, s33
	s_lshl_b32 s34, s10, 6
	v_readlane_b32 s0, v255, 34
	v_or_b32_e32 v2, s34, v105
	v_readlane_b32 s1, v255, 35
	v_or_b32_e32 v8, s72, v2
	s_bfe_u32 s24, s74, 0x10001
	v_mov_b64_e32 v[6:7], s[0:1]
	v_mad_i64_i32 v[2:3], s[0:1], v8, s44, v[6:7]
	v_or_b32_e32 v8, 32, v8
	v_or_b32_e32 v38, s72, v105
	s_lshl_b32 s52, s24, 8
	v_mad_i64_i32 v[8:9], s[0:1], v8, s44, v[6:7]
	v_mad_i64_i32 v[40:41], s[0:1], v38, s44, v[6:7]
	v_lshl_add_u64 v[2:3], v[2:3], 0, s[52:53]
	v_lshl_add_u64 v[8:9], v[8:9], 0, s[52:53]
	v_lshl_add_u64 v[6:7], v[40:41], 0, s[52:53]
	v_lshl_add_u64 v[2:3], v[2:3], 0, v[98:99]
	v_lshl_add_u64 v[10:11], v[8:9], 0, v[98:99]
	v_lshl_add_u64 v[6:7], v[6:7], 0, v[98:99]
	global_load_dwordx4 v[2:5], v[2:3], off offset:2560
	s_nop 0
	global_load_dwordx4 v[6:9], v[6:7], off offset:2048
	s_nop 0
	global_load_dwordx4 v[10:13], v[10:11], off offset:2560
	s_add_i32 s27, s34, 64
	s_lshl_b32 s2, s24, 7
	s_lshl_b32 s52, s2, 1
	v_ashrrev_i32_e32 v39, 31, v38
	v_cmp_gt_u32_e32 vcc, s27, v129
	s_and_saveexec_b64 s[0:1], vcc
	s_cbranch_execz .Lssd_l1
	v_readlane_b32 s4, v255, 34
	v_readlane_b32 s5, v255, 35
	v_or_b32_e32 v224, s72, v129
	s_nop 0
	v_mov_b64_e32 v[222:223], s[4:5]
	v_mad_i64_i32 v[222:223], s[4:5], v224, s44, v[222:223]
	v_lshl_add_u64 v[222:223], v[222:223], 0, s[52:53]
	v_lshl_add_u64 v[222:223], v[222:223], 0, v[98:99]
	global_load_dwordx4 v[204:207], v[222:223], off offset:2048
.Lssd_l1:
	s_or_b64 exec, exec, s[0:1]
	v_cmp_gt_u32_e32 vcc, s34, v105
	s_and_saveexec_b64 s[0:1], vcc
	s_cbranch_execz .Lssd_l2
	v_readlane_b32 s4, v255, 34
	v_readlane_b32 s5, v255, 35
	v_or_b32_e32 v224, 64, v38
	s_nop 0
	v_mov_b64_e32 v[222:223], s[4:5]
	v_mad_i64_i32 v[222:223], s[4:5], v224, s44, v[222:223]
	v_lshl_add_u64 v[222:223], v[222:223], 0, s[52:53]
	v_lshl_add_u64 v[222:223], v[222:223], 0, v[98:99]
	global_load_dwordx4 v[208:211], v[222:223], off offset:2048
.Lssd_l2:
	s_or_b64 exec, exec, s[0:1]
	v_cmp_gt_u32_e32 vcc, s27, v149
	s_and_saveexec_b64 s[0:1], vcc
	s_cbranch_execz .Lssd_l3
	v_readlane_b32 s4, v255, 34
	v_readlane_b32 s5, v255, 35
	v_add_u32_e32 v224, s72, v149
	s_nop 0
	v_mov_b64_e32 v[222:223], s[4:5]
	v_mad_i64_i32 v[222:223], s[4:5], v224, s44, v[222:223]
	v_lshl_add_u64 v[222:223], v[222:223], 0, s[52:53]
	v_lshl_add_u64 v[222:223], v[222:223], 0, v[98:99]
	global_load_dwordx4 v[214:217], v[222:223], off offset:2048
.Lssd_l3:
	s_or_b64 exec, exec, s[0:1]
	s_mov_b64 s[0:1], exec
	v_readlane_b32 s2, v255, 29
	v_readlane_b32 s3, v255, 30
	s_and_b64 s[2:3], s[0:1], s[2:3]
	s_mov_b64 exec, s[2:3]
	s_cbranch_execz .Lssd_l4
	s_lshl_b32 s2, s24, 5
	v_readlane_b32 s3, v255, 38
	v_or_b32_e32 v222, s72, v123
	s_add_u32 s2, s3, s2
	v_readlane_b32 s3, v255, 39
	v_ashrrev_i32_e32 v223, 31, v222
	s_addc_u32 s3, s3, 0
	v_lshlrev_b64 v[222:223], 6, v[222:223]
	v_lshl_add_u64 v[222:223], s[2:3], 0, v[222:223]
	v_mov_b32_e32 v113, v99
	v_lshl_add_u64 v[222:223], v[222:223], 0, v[112:113]
	global_load_dwordx4 v[218:221], v[222:223], off
.Lssd_l4:
	s_mov_b64 exec, s[0:1]
	s_waitcnt vmcnt(0)
	ds_write_b128 v127, v[2:5]
	ds_write_b128 v127, v[6:9] offset:17408
	ds_write_b128 v127, v[10:13] offset:8704
	v_cmp_gt_u32_e32 vcc, s27, v129
	s_and_saveexec_b64 s[0:1], vcc
	ds_write_b128 v127, v[204:207] offset:26112
	s_or_b64 exec, exec, s[0:1]
	v_cmp_gt_u32_e32 vcc, s34, v105
	s_and_saveexec_b64 s[0:1], vcc
	ds_write_b128 v127, v[208:211] offset:34816
	s_or_b64 exec, exec, s[0:1]
	v_cmp_gt_u32_e32 vcc, s27, v149
	s_and_saveexec_b64 s[0:1], vcc
	ds_write_b128 v127, v[214:217] offset:43520
	s_or_b64 exec, exec, s[0:1]
	s_mov_b64 s[0:1], exec
	v_readlane_b32 s2, v255, 29
	v_readlane_b32 s3, v255, 30
	s_and_b64 s[2:3], s[0:1], s[2:3]
	s_mov_b64 exec, s[2:3]
	ds_write_b128 v156, v[218:221]
